# compress-bias partial-sum loop: 8 weight loads in flight per iteration instead of one waited load at a time (same summation order)
# speedup vs baseline: 1.0207x; 1.0091x over previous
; DI void cvt_next(const Params& p, char* smem, int nl, int t) {
;     ...
;               int which = e >> 4, part = e & 15;
;               const float* pe = p.cmp_pe + (size_t)(nli * 2 + which) * 4096 + part * 256;
;               const float* w1 = p.cmp_w1 + ((size_t)(nli * 2 + which) * 4096 + part * 256) * 256 + tid;
;               float acc = 0.f;
; #pragma unroll 8
;               for (int k = 0; k < 256; ++k) acc += pe[k] * w1[(size_t)k * 256];
;               ((float*)(ws + WS_CMPB))[(which * 16 + part) * 256 + tid] = acc;
.LBB0_970:
	s_movk_i32 s15, 0xf000
	s_add_u32 s16, s13, s0
	v_add_co_u32_e32 v14, vcc, s15, v4
	s_addc_u32 s17, s14, s1
	s_nop 0
	v_addc_co_u32_e32 v15, vcc, -1, v5, vcc
	global_load_dwordx4 v[6:9], v1, s[16:17] offset:16
	global_load_dwordx4 v[10:13], v1, s[16:17]
	global_load_dword v3, v[14:15], off offset:-3072
	global_load_dword v16, v[14:15], off offset:-2048
	global_load_dword v17, v[14:15], off offset:-1024
	global_load_dword v18, v[4:5], off offset:-4096
	global_load_dword v19, v[4:5], off offset:-3072
	global_load_dword v20, v[4:5], off offset:-2048
	global_load_dword v21, v[4:5], off offset:-1024
	global_load_dword v22, v[4:5], off
	s_add_u32 s0, s0, 32
	s_mov_b64 s[16:17], 0x2000
	s_addc_u32 s1, s1, 0
	v_lshl_add_u64 v[4:5], v[4:5], 0, s[16:17]
	s_waitcnt vmcnt(0)
	v_fmac_f32_e32 v0, v10, v3
	v_fmac_f32_e32 v0, v11, v16
	v_fmac_f32_e32 v0, v12, v17
	v_fmac_f32_e32 v0, v13, v18
	v_fmac_f32_e32 v0, v6, v19
	v_fmac_f32_e32 v0, v7, v20
	v_fmac_f32_e32 v0, v8, v21
	v_fmac_f32_e32 v0, v9, v22
	s_cmpk_eq_i32 s0, 0x400
	s_cbranch_scc0 .LBB0_970
	v_lshl_add_u32 v4, s12, 8, v2
	v_readlane_b32 s0, v255, 28
	v_ashrrev_i32_e32 v5, 31, v4
	v_readlane_b32 s1, v255, 29
	s_nop 1
	v_lshl_add_u64 v[4:5], v[4:5], 2, s[0:1]
	s_mov_b64 s[0:1], 0
	global_store_dword v[4:5], v0, off
